# baseline (speedup 1.0000x reference)
; #define LAS __attribute__((address_space(3)))
; __device__ __forceinline__ void p0_prologue(const Params& p, LAS unsigned char* lds, int tid) {
;     ...
;     LAS unsigned* scr = (LAS unsigned*)(lds + wave * 8192);
;     const int gw = blockIdx.x * 8 + wave, NGW = gridDim.x * 8;
;     ...
;     for (int it = gw; it < I_LAYER * DEPTH; it += NGW) {
;         const int l = it / I_LAYER; int r = it % I_LAYER;
;         unsigned char* wl = p.ws + (size_t)l * LAYER_BYTES;
.LBB0_427:
	v_readlane_b32 s98, v254, 36
	v_readlane_b32 s99, v253, 34
	s_cmp_gt_u32 s98, 2
	s_cbranch_scc1 .Lmy_w_skip
	v_writelane_b32 v140, s0, 0
	v_writelane_b32 v140, s1, 1
	v_writelane_b32 v140, s2, 2
	v_writelane_b32 v140, s3, 3
	v_writelane_b32 v140, s4, 4
	v_writelane_b32 v140, s5, 5
	v_writelane_b32 v140, s6, 6
	v_writelane_b32 v140, s7, 7
	v_writelane_b32 v140, s8, 8
	v_writelane_b32 v140, s9, 9
	v_writelane_b32 v140, s10, 10
	v_writelane_b32 v140, s11, 11
	v_writelane_b32 v140, s12, 12
	v_writelane_b32 v140, s13, 13
	v_writelane_b32 v140, s14, 14
	v_writelane_b32 v140, s15, 15
	v_writelane_b32 v140, s16, 16
	v_writelane_b32 v140, s17, 17
	v_writelane_b32 v140, s18, 18
	v_writelane_b32 v140, s19, 19
	v_writelane_b32 v140, s20, 20
	v_writelane_b32 v140, s21, 21
	v_writelane_b32 v140, s22, 22
	v_writelane_b32 v140, s23, 23
	v_writelane_b32 v140, s24, 24
	v_writelane_b32 v140, s25, 25
	v_writelane_b32 v140, s26, 26
	v_writelane_b32 v140, s27, 27
	v_writelane_b32 v140, s28, 28
	v_writelane_b32 v140, s29, 29
	v_writelane_b32 v140, s30, 30
	v_writelane_b32 v140, s31, 31
	v_writelane_b32 v140, s32, 32
	v_writelane_b32 v140, s33, 33
	v_writelane_b32 v140, s34, 34
	v_writelane_b32 v140, s35, 35
	v_writelane_b32 v140, s36, 36
	v_writelane_b32 v140, s37, 37
	v_writelane_b32 v140, s38, 38
	v_writelane_b32 v140, s39, 39
	v_writelane_b32 v140, s40, 40
	v_writelane_b32 v140, s41, 41
	v_writelane_b32 v140, s42, 42
	v_writelane_b32 v140, s43, 43
	v_writelane_b32 v140, s44, 44
	v_writelane_b32 v140, s45, 45
	v_writelane_b32 v140, s46, 46
	v_writelane_b32 v140, s47, 47
	v_writelane_b32 v140, s48, 48
	v_writelane_b32 v140, s49, 49
	v_writelane_b32 v140, s50, 50
	v_writelane_b32 v140, s51, 51
	v_writelane_b32 v140, s52, 52
	v_writelane_b32 v140, s53, 53
	v_writelane_b32 v140, s54, 54
	v_writelane_b32 v140, s55, 55
	v_writelane_b32 v140, s56, 56
	v_writelane_b32 v140, s57, 57
	v_writelane_b32 v140, s58, 58
	v_writelane_b32 v140, s59, 59
	v_writelane_b32 v140, s60, 60
	v_writelane_b32 v140, s61, 61
	v_writelane_b32 v140, s62, 62
	v_writelane_b32 v140, s63, 63
	v_writelane_b32 v141, s64, 0
	v_writelane_b32 v141, s65, 1
	v_writelane_b32 v141, s66, 2
	v_writelane_b32 v141, s67, 3
	v_writelane_b32 v141, s68, 4
	v_writelane_b32 v141, s69, 5
	v_writelane_b32 v141, s70, 6
	v_writelane_b32 v141, s71, 7
	v_writelane_b32 v141, s72, 8
	v_writelane_b32 v141, s73, 9
	v_writelane_b32 v141, s74, 10
	v_writelane_b32 v141, s75, 11
	v_writelane_b32 v141, s76, 12
	v_writelane_b32 v141, s77, 13
	v_writelane_b32 v141, s78, 14
	v_writelane_b32 v141, s79, 15
	v_writelane_b32 v141, s80, 16
	v_writelane_b32 v141, s81, 17
	v_writelane_b32 v141, s82, 18
	v_writelane_b32 v141, s83, 19
	v_writelane_b32 v141, s84, 20
	v_writelane_b32 v141, s85, 21
	v_writelane_b32 v141, s86, 22
	v_writelane_b32 v141, s87, 23
	v_writelane_b32 v141, s88, 24
	v_writelane_b32 v141, s89, 25
	v_writelane_b32 v141, s90, 26
	v_writelane_b32 v141, s91, 27
	v_writelane_b32 v141, s92, 28
	v_writelane_b32 v141, s93, 29
	v_writelane_b32 v141, s94, 30
	v_writelane_b32 v141, s95, 31
	v_writelane_b32 v141, s96, 32
	v_writelane_b32 v141, s97, 33
	s_add_i32 s98, s98, 1
	s_mul_i32 s98, s98, 0x2a00
	s_cmp_lt_u32 s99, 64
	s_cbranch_scc1 .Lmy_w_small
	s_sub_i32 s1, s99, 64
	s_lshl_b32 s1, s1, 3
	s_add_i32 s0, s98, s1
	s_add_i32 s98, s98, 9728
	s_movk_i32 s10, 0x600
	s_branch .Lmy_w_go
.Lmy_w_small:
	s_lshl_b32 s1, s99, 3
	s_add_i32 s0, s98, s1
	s_add_i32 s0, s0, 9728
	s_add_i32 s98, s98, 0x2a00
	s_movk_i32 s10, 0x200
.Lmy_w_go:
	v_and_b32_e32 v34, 63, v201
	v_lshrrev_b32_e32 v35, 6, v201
	v_lshlrev_b32_e32 v36, 3, v201
	v_add_u32_e32 v90, s0, v35
	s_add_i32 s99, s98, -1
	v_readlane_b32 s62, v255, 8
	v_readlane_b32 s63, v255, 9
	s_branch .Lmy_w_entry
